# layer 0: the 192 workgroups without a third attention unit each run one of the last 192 prep items in that idle tail; the prep ticket loop stops at item 960
# speedup vs baseline: 1.0256x; 1.0027x over previous
.LBB0_394:
	s_mov_b32 s100, 0
	s_cmpk_ge_i32 s90, 0x160
	s_cbranch_scc1 prep_items_l0
	s_mov_b64 s[98:99], s[14:15]
	s_branch .LBB0_424
prep_items_l0:
	s_add_u32 s6, s34, 0x1c4000
	s_addc_u32 s7, s35, 0
	s_add_u32 s8, s34, 0x1c2000
	s_addc_u32 s9, s35, 0
	s_add_u32 s10, s34, 0x1c6000
	s_addc_u32 s11, s35, 0
	s_add_u32 s70, s34, 0xda000
	s_addc_u32 s71, s35, 0
	s_add_i32 s4, 0, 0x20180
	s_mov_b32 s73, 0
	v_mov_b32_e32 v123, 0
	v_mov_b32_e32 v1, s4
	s_movk_i32 s5, 0x47f
	s_movk_i32 s19, 0x90
	s_movk_i32 s22, 0x3800
	s_movk_i32 s23, 0xc00
	s_movk_i32 s27, 0x800
	s_mov_b32 s33, 0xffff0000
	s_movk_i32 s44, 0x7fff
	v_mov_b32_e32 v127, 0x358637bd
	s_mov_b32 s45, 0xf800000
	v_mov_b32_e32 v129, 0x260
	s_movk_i32 s48, 0x110
	s_cmpk_lg_i32 s94, 0x100
	s_cbranch_scc1 it_mode_done_l0
	s_cmp_lg_u32 s100, 0
	s_cbranch_scc1 it_mode_done_l0
	s_movk_i32 s5, 0x3bf
it_mode_done_l0:
	s_branch .LBB0_397

.LBB0_396:
	s_and_b64 vcc, exec, s[0:1]
	s_cbranch_vccnz items_exit_l0
.LBB0_397:
	v_mov_b32_e32 v2, v0
	s_nop 0
	v_cmp_eq_u32_e32 vcc, 0, v2
	s_and_saveexec_b64 s[0:1], vcc
	s_cbranch_execz .LBB0_401
	s_mov_b64 s[76:77], exec
	v_mbcnt_lo_u32_b32 v2, s76, 0
	v_mbcnt_hi_u32_b32 v2, s77, v2
	v_cmp_eq_u32_e32 vcc, 0, v2
	s_and_saveexec_b64 s[74:75], vcc
	s_cbranch_execz .LBB0_400
	s_cmp_lg_u32 s100, 0
	s_cbranch_scc1 it_tail_tk_l0
	s_bcnt1_i32_b64 s3, s[76:77]
	v_mov_b32_e32 v3, s3
	global_atomic_add v3, v123, v3, s[34:35] offset:2048 sc0
	s_branch it_tk_join_l0
it_tail_tk_l0:
	v_mov_b32_e32 v3, s101
	s_movk_i32 s101, 0x7fff
it_tk_join_l0:
.LBB0_400:
	s_or_b64 exec, exec, s[74:75]
	s_waitcnt vmcnt(0)
	v_readfirstlane_b32 s3, v3
	v_mov_b32_e32 v3, s4
	s_nop 0
	v_add_u32_e32 v2, s3, v2
	ds_write_b32 v3, v2

items_exit_l0:
	s_cmp_lg_u32 s100, 0
	s_cbranch_scc0 .LBB0_437
	s_mov_b32 s100, 0
	s_branch attn_tail_done_l0

.LBB0_568:
	s_cmpk_lg_i32 s94, 0x100
	s_cbranch_scc1 attn_tail_done_l0
	s_and_b32 s101, s2, 7
	s_cmpk_lt_u32 s101, 2
	s_cbranch_scc1 attn_tail_done_l0
	s_add_i32 s101, s101, -2
	s_lshl_b32 s101, s101, 5
	s_lshr_b32 s100, s2, 3
	s_add_i32 s101, s101, s100
	s_addk_i32 s101, 0x3c0
	s_mov_b32 s100, 1
	s_add_u32 s14, s34, 0x5900000
	s_addc_u32 s15, s35, 0
	s_add_u32 s52, s34, 0x8f00000
	s_addc_u32 s53, s35, 0
	s_add_u32 s68, s34, 0x1c0000
	s_addc_u32 s69, s35, 0
	s_branch prep_items_l0
attn_tail_done_l0:
	s_mov_b64 s[6:7], s[64:65]
	s_getreg_b32 s4, hwreg(HW_REG_XCC_ID, 0, 4)
	s_waitcnt vmcnt(0)
	s_barrier
	s_mov_b64 s[0:1], exec
	v_readlane_b32 s8, v250, 4
	v_readlane_b32 s9, v250, 5
	s_and_b64 s[8:9], s[0:1], s[8:9]
	s_mov_b64 exec, s[8:9]
	s_cbranch_execz .LBB0_620
	s_add_i32 s3, 0, 0x20160
	v_mov_b32_e32 v1, s3
	s_waitcnt vmcnt(0) expcnt(0) lgkmcnt(0)
	ds_read_b32 v3, v1
	s_add_i32 s3, 0, 0x20164
	v_mov_b32_e32 v1, s3
	ds_read_b32 v1, v1
	s_and_b32 s4, s4, 15
	s_waitcnt lgkmcnt(1)
	v_cmp_ne_u32_e32 vcc, 0, v3
	s_cbranch_vccnz .LBB0_584
	v_readlane_b32 s8, v250, 6
	v_readlane_b32 s9, v250, 7
	s_load_dwordx2 s[12:13], s[8:9], 0x4
	s_add_u32 s8, s6, 0x1000
	s_addc_u32 s9, s7, 0
	s_add_u32 s10, s6, 0x1100
	s_addc_u32 s11, s7, 0
	s_add_u32 s14, s6, 0x1200
	s_addc_u32 s15, s7, 0
	s_waitcnt lgkmcnt(0)
	s_mul_i32 s5, s12, s94
	s_add_u32 s52, s6, 0x1300
	s_mul_i32 s5, s5, s13
	s_addc_u32 s53, s7, 0
	s_mov_b32 s12, 1
	v_mov_b32_e32 v17, 0
	s_branch .LBB0_572
